# MLA S1 tail of the second tile of each pair: row-max as two interleaved v_max3 chains, NaN-canonicalising v_max x,x removed
# baseline (speedup 1.0000x reference)
; #define QSTEP(d, A, B, NA, NB) do { if ((d) + 2 < 12) { NA = KLD((d) + 2, 0); NB = KLD((d) + 2, 1); } SBAR(); \
;     p0 = __builtin_amdgcn_mfma_f32_32x32x16_bf16(A, qr[d], p0, 0, 0, 0); p1 = __builtin_amdgcn_mfma_f32_32x32x16_bf16(B, qr[d], p1, 0, 0, 0); SBAR(); } while (0)
; __device__ __forceinline__ void partialSM(f32x16& p0, f32x16& p1, float& m_reg, float& mn, float& alpha) {
;   constexpr float C = SCALE * 1.4426950408889634f;
;   float pmax = p0[0];
; #pragma unroll
;   for (int r = 1; r < 16; ++r) pmax = fmaxf(pmax, p0[r]);
; #pragma unroll
;   for (int r = 0; r < 16; ++r) pmax = fmaxf(pmax, p1[r]);
;   { auto rr = __builtin_amdgcn_permlane32_swap(__float_as_uint(pmax), __float_as_uint(pmax), false, false);
;     pmax = fmaxf(__uint_as_float(rr[0]), __uint_as_float(rr[1])); }
;   if (__builtin_expect(__all(pmax - m_reg <= THR / SCALE), 1)) { mn = m_reg; alpha = 1.f; }
;   else { mn = fmaxf(m_reg, pmax); alpha = __builtin_amdgcn_exp2f((m_reg - mn) * C); m_reg = mn; }
; __device__ __forceinline__ void qkt2(f32x16& p0, f32x16& p1, const char* Ks, const bf16x8* qr, const int* kb4) {
;     ...
;   p0 = f32x16{}; p1 = f32x16{};
;   bf16x8 a0 = KLD(0, 0), b0 = KLD(0, 1), a1 = KLD(1, 0), b1 = KLD(1, 1), a2, b2;
;     ...
;   QSTEP(0, a0, b0, a2, b2); QSTEP(1, a1, b1, a0, b0); QSTEP(2, a2, b2, a1, b1);
;   QSTEP(3, a0, b0, a2, b2); QSTEP(4, a1, b1, a0, b0); QSTEP(5, a2, b2, a1, b1);
;   QSTEP(6, a0, b0, a2, b2); QSTEP(7, a1, b1, a0, b0); QSTEP(8, a2, b2, a1, b1);
;   QSTEP(9, a0, b0, a2, b2); QSTEP(10, a1, b1, a0, b0); QSTEP(11, a2, b2, a1, b1);
;     ...
; }
.LBB0_447:
	s_waitcnt lgkmcnt(5)
	v_mfma_f32_32x32x16_bf16 v[80:95], v[194:197], v[112:115], v[80:95]
	v_mfma_f32_32x32x16_bf16 v[64:79], v[224:227], v[112:115], v[64:79]
	ds_read_b128 v[194:197], v207 offset:57472
	ds_read_b128 v[224:227], v219 offset:12416
	s_waitcnt lgkmcnt(4)
	v_mfma_f32_32x32x16_bf16 v[80:95], v[228:231], v[116:119], v[80:95]
	v_mfma_f32_32x32x16_bf16 v[64:79], v[232:235], v[116:119], v[64:79]
	ds_read_b128 v[228:231], v210 offset:57600
	ds_read_b128 v[232:235], v216 offset:12544
	s_waitcnt lgkmcnt(4)
	v_mfma_f32_32x32x16_bf16 v[80:95], v[236:239], v[120:123], v[80:95]
	v_mfma_f32_32x32x16_bf16 v[64:79], v[240:243], v[120:123], v[64:79]
	ds_read_b128 v[236:239], v209 offset:57600
	ds_read_b128 v[240:243], v217 offset:12544
	s_waitcnt lgkmcnt(4)
	v_mfma_f32_32x32x16_bf16 v[80:95], v[194:197], v[124:127], v[80:95]
	v_mfma_f32_32x32x16_bf16 v[64:79], v[224:227], v[124:127], v[64:79]
	ds_read_b128 v[194:197], v208 offset:57600
	ds_read_b128 v[224:227], v218 offset:12544
	s_waitcnt lgkmcnt(4)
	v_mfma_f32_32x32x16_bf16 v[80:95], v[228:231], v[132:135], v[80:95]
	v_mfma_f32_32x32x16_bf16 v[64:79], v[232:235], v[132:135], v[64:79]
	ds_read_b128 v[228:231], v207 offset:57600
	ds_read_b128 v[232:235], v219 offset:12544
	s_waitcnt lgkmcnt(4)
	v_mfma_f32_32x32x16_bf16 v[80:95], v[236:239], v[140:143], v[80:95]
	v_mfma_f32_32x32x16_bf16 v[64:79], v[240:243], v[140:143], v[64:79]
	s_waitcnt lgkmcnt(2)
	v_mfma_f32_32x32x16_bf16 v[80:95], v[194:197], v[128:131], v[80:95]
	v_mfma_f32_32x32x16_bf16 v[64:79], v[224:227], v[128:131], v[64:79]
	s_waitcnt lgkmcnt(0)
	v_mfma_f32_32x32x16_bf16 v[80:95], v[228:231], v[136:139], v[80:95]
	v_mfma_f32_32x32x16_bf16 v[64:79], v[232:235], v[136:139], v[64:79]
	s_nop 9
	v_max3_f32 v194, v80, v81, v82
	v_max3_f32 v194, v194, v83, v84
	v_max3_f32 v195, v64, v65, v66
	v_max3_f32 v194, v194, v85, v86
	v_max3_f32 v195, v195, v67, v68
	v_max3_f32 v194, v194, v87, v88
	v_max3_f32 v195, v195, v69, v70
	v_max3_f32 v194, v194, v89, v90
	v_max3_f32 v195, v195, v71, v72
	v_max3_f32 v194, v194, v91, v92
	v_max3_f32 v195, v195, v73, v74
	v_max3_f32 v194, v194, v93, v94
	v_max3_f32 v195, v195, v75, v76
	v_max3_f32 v195, v195, v77, v78
	v_max3_f32 v194, v194, v95, v79
	v_max_f32_e32 v194, v194, v195
	v_mov_b32_e32 v195, v194
	s_nop 1
	v_permlane32_swap_b32_e32 v194, v195
	v_max_f32_e32 v194, v194, v195
	v_max_f32_e32 v195, v220, v220
	v_max_f32_e32 v195, v195, v194
	v_sub_f32_e32 v196, v194, v220
	v_sub_f32_e32 v194, v220, v195
	v_mul_f32_e32 v194, 0x3dd53b94, v194
	v_exp_f32_e32 v194, v194
	v_cmp_ge_f32_e32 vcc, s30, v196
	s_cmp_eq_u64 vcc, exec
	s_cselect_b64 s[8:9], -1, 0
	s_waitcnt lgkmcnt(0)
	s_barrier
	v_cndmask_b32_e64 v194, v194, 1.0, s[8:9]
	v_cmp_gt_f32_e32 vcc, 1.0, v194
	s_cbranch_vccz .LBB0_451
	s_and_saveexec_b64 s[0:1], s[6:7]
	ds_write_b32 v205, v194 offset:128
	s_or_b64 exec, exec, s[0:1]
	s_waitcnt lgkmcnt(0)
	v_add_u32_e32 v196, s3, v184
	ds_read_b128 v[224:227], v196 offset:224
	ds_read_b128 v[228:231], v196 offset:192
	ds_read_b128 v[232:235], v196 offset:160
	ds_read_b128 v[236:239], v196 offset:128
	s_waitcnt lgkmcnt(3)
	v_pk_mul_f32 v[12:13], v[12:13], v[224:225]
	s_waitcnt lgkmcnt(2)
	v_pk_mul_f32 v[8:9], v[8:9], v[228:229]
	s_waitcnt lgkmcnt(1)
	v_pk_mul_f32 v[4:5], v[4:5], v[232:233]
	v_pk_mul_f32 v[14:15], v[14:15], v[226:227]
	v_pk_mul_f32 v[10:11], v[10:11], v[230:231]
	v_pk_mul_f32 v[6:7], v[6:7], v[234:235]
	s_waitcnt lgkmcnt(0)
	v_pk_mul_f32 v[2:3], v[2:3], v[238:239]
	v_pk_mul_f32 v[0:1], v[0:1], v[236:237]
	v_pk_mul_f32 v[60:61], v[60:61], v[224:225]
	v_pk_mul_f32 v[56:57], v[56:57], v[228:229]
	v_pk_mul_f32 v[52:53], v[52:53], v[232:233]
	v_pk_mul_f32 v[62:63], v[62:63], v[226:227]
	v_pk_mul_f32 v[58:59], v[58:59], v[230:231]
	v_pk_mul_f32 v[54:55], v[54:55], v[234:235]
	v_pk_mul_f32 v[50:51], v[50:51], v[238:239]
	v_pk_mul_f32 v[48:49], v[48:49], v[236:237]
	v_pk_mul_f32 v[44:45], v[44:45], v[224:225]
	v_pk_mul_f32 v[40:41], v[40:41], v[228:229]
	v_pk_mul_f32 v[36:37], v[36:37], v[232:233]
	v_pk_mul_f32 v[46:47], v[46:47], v[226:227]
	v_pk_mul_f32 v[42:43], v[42:43], v[230:231]
	v_pk_mul_f32 v[38:39], v[38:39], v[234:235]
	v_pk_mul_f32 v[34:35], v[34:35], v[238:239]
	v_pk_mul_f32 v[32:33], v[32:33], v[236:237]
	v_pk_mul_f32 v[28:29], v[28:29], v[224:225]
	v_pk_mul_f32 v[24:25], v[24:25], v[228:229]
	v_pk_mul_f32 v[20:21], v[20:21], v[232:233]
	v_pk_mul_f32 v[30:31], v[30:31], v[226:227]
	v_pk_mul_f32 v[26:27], v[26:27], v[230:231]
	v_pk_mul_f32 v[22:23], v[22:23], v[234:235]
	v_pk_mul_f32 v[18:19], v[18:19], v[238:239]
	v_pk_mul_f32 v[16:17], v[16:17], v[236:237]

; #define QSTEP(d, A, B, NA, NB) do { if ((d) + 2 < 12) { NA = KLD((d) + 2, 0); NB = KLD((d) + 2, 1); } SBAR(); \
;     p0 = __builtin_amdgcn_mfma_f32_32x32x16_bf16(A, qr[d], p0, 0, 0, 0); p1 = __builtin_amdgcn_mfma_f32_32x32x16_bf16(B, qr[d], p1, 0, 0, 0); SBAR(); } while (0)
; __device__ __forceinline__ void partialSM(f32x16& p0, f32x16& p1, float& m_reg, float& mn, float& alpha) {
;   constexpr float C = SCALE * 1.4426950408889634f;
;   float pmax = p0[0];
; #pragma unroll
;   for (int r = 1; r < 16; ++r) pmax = fmaxf(pmax, p0[r]);
; #pragma unroll
;   for (int r = 0; r < 16; ++r) pmax = fmaxf(pmax, p1[r]);
;   { auto rr = __builtin_amdgcn_permlane32_swap(__float_as_uint(pmax), __float_as_uint(pmax), false, false);
;     pmax = fmaxf(__uint_as_float(rr[0]), __uint_as_float(rr[1])); }
;   if (__builtin_expect(__all(pmax - m_reg <= THR / SCALE), 1)) { mn = m_reg; alpha = 1.f; }
;   else { mn = fmaxf(m_reg, pmax); alpha = __builtin_amdgcn_exp2f((m_reg - mn) * C); m_reg = mn; }
; __device__ __forceinline__ void qkt2(f32x16& p0, f32x16& p1, const char* Ks, const bf16x8* qr, const int* kb4) {
;     ...
;   p0 = f32x16{}; p1 = f32x16{};
;   bf16x8 a0 = KLD(0, 0), b0 = KLD(0, 1), a1 = KLD(1, 0), b1 = KLD(1, 1), a2, b2;
;     ...
;   QSTEP(0, a0, b0, a2, b2); QSTEP(1, a1, b1, a0, b0); QSTEP(2, a2, b2, a1, b1);
;   QSTEP(3, a0, b0, a2, b2); QSTEP(4, a1, b1, a0, b0); QSTEP(5, a2, b2, a1, b1);
;   QSTEP(6, a0, b0, a2, b2); QSTEP(7, a1, b1, a0, b0); QSTEP(8, a2, b2, a1, b1);
;   QSTEP(9, a0, b0, a2, b2); QSTEP(10, a1, b1, a0, b0); QSTEP(11, a2, b2, a1, b1);
;     ...
; }
.LBB0_453:
	ds_read_b128 v[64:67], v210 offset:32768
	ds_read_b128 v[68:71], v210 offset:45056
	s_waitcnt vmcnt(4)
	ds_read_b128 v[164:167], v209 offset:32768
	s_waitcnt vmcnt(3)
	ds_read_b128 v[168:171], v209 offset:45056
	s_waitcnt vmcnt(2)
	ds_read_b128 v[172:175], v208 offset:32768
	s_waitcnt vmcnt(1)
	ds_read_b128 v[176:179], v208 offset:45056
	s_waitcnt lgkmcnt(5)
	v_mfma_f32_32x32x16_bf16 v[80:95], v[64:67], v[96:99], 0
	s_waitcnt lgkmcnt(4)
	v_mfma_f32_32x32x16_bf16 v[64:79], v[68:71], v[96:99], 0
	s_waitcnt vmcnt(0)
	ds_read_b128 v[180:183], v207 offset:32768
	ds_read_b128 v[190:193], v207 offset:45056
	s_waitcnt lgkmcnt(5)
	v_mfma_f32_32x32x16_bf16 v[80:95], v[164:167], v[100:103], v[80:95]
	s_waitcnt lgkmcnt(4)
	v_mfma_f32_32x32x16_bf16 v[64:79], v[168:171], v[100:103], v[64:79]
	ds_read_b128 v[164:167], v210 offset:32896
	ds_read_b128 v[168:171], v210 offset:45184
	s_waitcnt lgkmcnt(5)
	v_mfma_f32_32x32x16_bf16 v[80:95], v[172:175], v[104:107], v[80:95]
	s_waitcnt lgkmcnt(4)
	v_mfma_f32_32x32x16_bf16 v[64:79], v[176:179], v[104:107], v[64:79]
	ds_read_b128 v[172:175], v209 offset:32896
	ds_read_b128 v[176:179], v209 offset:45184
	s_waitcnt lgkmcnt(5)
	v_mfma_f32_32x32x16_bf16 v[80:95], v[180:183], v[108:111], v[80:95]
	s_waitcnt lgkmcnt(4)
	v_mfma_f32_32x32x16_bf16 v[64:79], v[190:193], v[108:111], v[64:79]
	ds_read_b128 v[180:183], v208 offset:32896
	ds_read_b128 v[190:193], v208 offset:45184
	s_waitcnt lgkmcnt(5)
	v_mfma_f32_32x32x16_bf16 v[80:95], v[164:167], v[112:115], v[80:95]
	s_waitcnt lgkmcnt(4)
	v_mfma_f32_32x32x16_bf16 v[64:79], v[168:171], v[112:115], v[64:79]
	ds_read_b128 v[164:167], v207 offset:32896
	ds_read_b128 v[168:171], v207 offset:45184
	s_waitcnt lgkmcnt(5)
	v_mfma_f32_32x32x16_bf16 v[80:95], v[172:175], v[116:119], v[80:95]
	s_waitcnt lgkmcnt(4)
	v_mfma_f32_32x32x16_bf16 v[64:79], v[176:179], v[116:119], v[64:79]
	ds_read_b128 v[172:175], v210 offset:33024
	ds_read_b128 v[176:179], v210 offset:45312
	s_waitcnt lgkmcnt(5)
	v_mfma_f32_32x32x16_bf16 v[80:95], v[180:183], v[120:123], v[80:95]
	s_waitcnt lgkmcnt(4)
	v_mfma_f32_32x32x16_bf16 v[64:79], v[190:193], v[120:123], v[64:79]
	ds_read_b128 v[180:183], v209 offset:33024
	ds_read_b128 v[190:193], v209 offset:45312
	s_waitcnt lgkmcnt(5)
	v_mfma_f32_32x32x16_bf16 v[80:95], v[164:167], v[124:127], v[80:95]
	s_waitcnt lgkmcnt(4)
	v_mfma_f32_32x32x16_bf16 v[64:79], v[168:171], v[124:127], v[64:79]
	ds_read_b128 v[164:167], v208 offset:33024
	ds_read_b128 v[168:171], v208 offset:45312
	s_waitcnt lgkmcnt(5)
	v_mfma_f32_32x32x16_bf16 v[80:95], v[172:175], v[132:135], v[80:95]
	s_waitcnt lgkmcnt(4)
	v_mfma_f32_32x32x16_bf16 v[64:79], v[176:179], v[132:135], v[64:79]
	ds_read_b128 v[172:175], v207 offset:33024
	ds_read_b128 v[176:179], v207 offset:45312
	s_waitcnt lgkmcnt(5)
	v_mfma_f32_32x32x16_bf16 v[80:95], v[180:183], v[140:143], v[80:95]
	s_waitcnt lgkmcnt(4)
	v_mfma_f32_32x32x16_bf16 v[64:79], v[190:193], v[140:143], v[64:79]
	s_waitcnt lgkmcnt(3)
	v_mfma_f32_32x32x16_bf16 v[80:95], v[164:167], v[128:131], v[80:95]
	s_waitcnt lgkmcnt(2)
	v_mfma_f32_32x32x16_bf16 v[64:79], v[168:171], v[128:131], v[64:79]
	s_waitcnt lgkmcnt(1)
	v_mfma_f32_32x32x16_bf16 v[80:95], v[172:175], v[136:139], v[80:95]
	s_waitcnt lgkmcnt(0)
	v_mfma_f32_32x32x16_bf16 v[64:79], v[176:179], v[136:139], v[64:79]
	s_nop 9
	v_max3_f32 v164, v80, v81, v82
	v_max3_f32 v164, v164, v83, v84
	v_max3_f32 v165, v64, v65, v66
	v_max3_f32 v164, v164, v85, v86
	v_max3_f32 v165, v165, v67, v68
	v_max3_f32 v164, v164, v87, v88
	v_max3_f32 v165, v165, v69, v70
	v_max3_f32 v164, v164, v89, v90
	v_max3_f32 v165, v165, v71, v72
	v_max3_f32 v164, v164, v91, v92
	v_max3_f32 v165, v165, v73, v74
	v_max3_f32 v164, v164, v93, v94
	v_max3_f32 v165, v165, v75, v76
	v_max3_f32 v165, v165, v77, v78
	v_max3_f32 v164, v164, v95, v79
	v_max_f32_e32 v164, v164, v165
	v_mov_b32_e32 v165, v164
	s_nop 1
	v_permlane32_swap_b32_e32 v164, v165
	v_max_f32_e32 v164, v164, v165
	v_max_f32_e32 v165, v220, v220
	v_max_f32_e32 v165, v165, v164
	v_sub_f32_e32 v166, v164, v220
	v_sub_f32_e32 v164, v220, v165
	v_mul_f32_e32 v164, 0x3dd53b94, v164
	v_exp_f32_e32 v164, v164
	v_cmp_ge_f32_e32 vcc, s30, v166
	s_cmp_eq_u64 vcc, exec
	s_cselect_b64 s[8:9], -1, 0
	s_waitcnt lgkmcnt(0)
	s_barrier
	v_cndmask_b32_e64 v164, v164, 1.0, s[8:9]
	v_cmp_gt_f32_e32 vcc, 1.0, v164
	s_cbranch_vccz .LBB0_457
	s_and_saveexec_b64 s[0:1], s[6:7]
	ds_write_b32 v205, v164 offset:128
	s_or_b64 exec, exec, s[0:1]
	s_waitcnt lgkmcnt(0)
	v_add_u32_e32 v178, s3, v184
	ds_read_b128 v[166:169], v178 offset:224
	ds_read_b128 v[170:173], v178 offset:192
	ds_read_b128 v[174:177], v178 offset:160
	ds_read_b128 v[178:181], v178 offset:128
	s_waitcnt lgkmcnt(3)
	v_pk_mul_f32 v[12:13], v[12:13], v[166:167]
	s_waitcnt lgkmcnt(2)
	v_pk_mul_f32 v[8:9], v[8:9], v[170:171]
	s_waitcnt lgkmcnt(1)
	v_pk_mul_f32 v[4:5], v[4:5], v[174:175]
	v_pk_mul_f32 v[14:15], v[14:15], v[168:169]
	v_pk_mul_f32 v[10:11], v[10:11], v[172:173]
	v_pk_mul_f32 v[6:7], v[6:7], v[176:177]
	s_waitcnt lgkmcnt(0)
	v_pk_mul_f32 v[2:3], v[2:3], v[180:181]
	v_pk_mul_f32 v[0:1], v[0:1], v[178:179]
	v_pk_mul_f32 v[60:61], v[60:61], v[166:167]
	v_pk_mul_f32 v[56:57], v[56:57], v[170:171]
	v_pk_mul_f32 v[52:53], v[52:53], v[174:175]
	v_pk_mul_f32 v[62:63], v[62:63], v[168:169]
	v_pk_mul_f32 v[58:59], v[58:59], v[172:173]
	v_pk_mul_f32 v[54:55], v[54:55], v[176:177]
	v_pk_mul_f32 v[50:51], v[50:51], v[180:181]
	v_pk_mul_f32 v[48:49], v[48:49], v[178:179]
	v_pk_mul_f32 v[44:45], v[44:45], v[166:167]
	v_pk_mul_f32 v[40:41], v[40:41], v[170:171]
	v_pk_mul_f32 v[36:37], v[36:37], v[174:175]
	v_pk_mul_f32 v[46:47], v[46:47], v[168:169]
	v_pk_mul_f32 v[42:43], v[42:43], v[172:173]
	v_pk_mul_f32 v[38:39], v[38:39], v[176:177]
	v_pk_mul_f32 v[34:35], v[34:35], v[180:181]
	v_pk_mul_f32 v[32:33], v[32:33], v[178:179]
	v_pk_mul_f32 v[28:29], v[28:29], v[166:167]
	v_pk_mul_f32 v[24:25], v[24:25], v[170:171]
	v_pk_mul_f32 v[20:21], v[20:21], v[174:175]
	v_pk_mul_f32 v[30:31], v[30:31], v[168:169]
	v_pk_mul_f32 v[26:27], v[26:27], v[172:173]
	v_pk_mul_f32 v[22:23], v[22:23], v[176:177]
	v_pk_mul_f32 v[18:19], v[18:19], v[180:181]
	v_pk_mul_f32 v[16:17], v[16:17], v[178:179]

; #define SBAR() __builtin_amdgcn_sched_barrier(0)
; __device__ __forceinline__ void partialSM(f32x16& p0, f32x16& p1, float& m_reg, float& mn, float& alpha) {
;     ...
;   float mnC = -mn * C;
; #pragma unroll
;   for (int r = 0; r < 16; ++r) p0[r] = fmaf(p0[r], C, mnC);
; #pragma unroll
;   for (int r = 0; r < 16; ++r) p1[r] = fmaf(p1[r], C, mnC);
; #pragma unroll
;   for (int r = 0; r < 16; ++r) p0[r] = __builtin_amdgcn_exp2f(p0[r]);
; }
; __device__ __forceinline__ void finishSM(f32x16& p0, f32x16& p1, float alpha, float& l_reg, bf16x8& pa0, bf16x8& pa1, bf16x8& pa2, bf16x8& pa3) {
; #pragma unroll
;   for (int r = 0; r < 16; ++r) p1[r] = __builtin_amdgcn_exp2f(p1[r]);
;   float ps = 0;
; #pragma unroll
;   for (int r = 0; r < 16; ++r) ps += p0[r];
; #pragma unroll
;   for (int r = 0; r < 16; ++r) ps += p1[r];
;   { auto rr = __builtin_amdgcn_permlane32_swap(__float_as_uint(ps), __float_as_uint(ps), false, false);
;     ps = __uint_as_float(rr[0]) + __uint_as_float(rr[1]); }
;   l_reg = l_reg * alpha + ps;
;     ...
;   PK4(p0, 0, pa0); PK4(p0, 8, pa1); PK4(p1, 0, pa2); PK4(p1, 8, pa3);
;     ...
; }
; __device__ __forceinline__ void pv2(f32x16* o, int vb, bf16x8 pa0, bf16x8 pa1, bf16x8 pa2, bf16x8 pa3) {
;   VSet X, Y;
;   SBAR(); v_issue<0>(X, vb); v_issue<1>(Y, vb);
;   asm volatile("s_waitcnt lgkmcnt(8)" ::: "memory"); SBAR(); v_mma(o[0], X, pa0, pa1, pa2, pa3); SBAR();
;   v_issue<2>(X, vb);
;   asm volatile("s_waitcnt lgkmcnt(8)" ::: "memory"); SBAR(); v_mma(o[1], Y, pa0, pa1, pa2, pa3); SBAR();
;   v_issue<3>(Y, vb);
;   asm volatile("s_waitcnt lgkmcnt(8)" ::: "memory"); SBAR(); v_mma(o[2], X, pa0, pa1, pa2, pa3); SBAR();
;   asm volatile("s_waitcnt lgkmcnt(0)" ::: "memory"); SBAR(); v_mma(o[3], Y, pa0, pa1, pa2, pa3); SBAR();
; }
.LBB0_463:
	v_cndmask_b32_e64 v178, v90, v178, s[8:9]
	v_mul_f32_e32 v90, 0xbdd53b94, v178
	v_fmamk_f32 v64, v64, 0x3dd53b94, v90
	v_fmamk_f32 v65, v65, 0x3dd53b94, v90
	v_exp_f32_e32 v64, v64
	v_fmamk_f32 v66, v66, 0x3dd53b94, v90
	v_exp_f32_e32 v65, v65
	v_fmamk_f32 v67, v67, 0x3dd53b94, v90
	v_exp_f32_e32 v66, v66
	v_fmamk_f32 v68, v68, 0x3dd53b94, v90
	v_fmamk_f32 v73, v73, 0x3dd53b94, v90
	v_exp_f32_e32 v67, v67
	v_fmamk_f32 v69, v69, 0x3dd53b94, v90
	v_fmamk_f32 v92, v187, 0x3dd53b94, v90
	v_exp_f32_e32 v68, v68
	v_exp_f32_e32 v187, v73
	v_add_f32_e32 v73, 0, v64
	v_fmamk_f32 v70, v70, 0x3dd53b94, v90
	v_exp_f32_e32 v69, v69
	v_add_f32_e32 v73, v65, v73
	v_fmamk_f32 v71, v71, 0x3dd53b94, v90
	v_exp_f32_e32 v70, v70
	v_add_f32_e32 v73, v66, v73
	v_fmamk_f32 v91, v186, 0x3dd53b94, v90
	v_exp_f32_e32 v71, v71
	v_add_f32_e32 v73, v67, v73
	v_fmamk_f32 v93, v182, 0x3dd53b94, v90
	v_fmamk_f32 v94, v183, 0x3dd53b94, v90
	v_fmamk_f32 v95, v180, 0x3dd53b94, v90
	v_fmamk_f32 v180, v181, 0x3dd53b94, v90
	v_fmamk_f32 v78, v78, 0x3dd53b94, v90
	v_fmamk_f32 v79, v79, 0x3dd53b94, v90
	v_fmamk_f32 v80, v80, 0x3dd53b94, v90
	v_fmamk_f32 v81, v81, 0x3dd53b94, v90
	v_fmamk_f32 v82, v82, 0x3dd53b94, v90
	v_fmamk_f32 v83, v83, 0x3dd53b94, v90
	v_fmamk_f32 v84, v84, 0x3dd53b94, v90
	v_fmamk_f32 v85, v85, 0x3dd53b94, v90
	v_fmamk_f32 v86, v86, 0x3dd53b94, v90
	v_fmamk_f32 v87, v87, 0x3dd53b94, v90
	v_fmamk_f32 v88, v88, 0x3dd53b94, v90
	v_fmamk_f32 v89, v89, 0x3dd53b94, v90
	v_fmamk_f32 v76, v76, 0x3dd53b94, v90
	v_fmamk_f32 v77, v77, 0x3dd53b94, v90
	v_fmamk_f32 v74, v74, 0x3dd53b94, v90
	v_fmamk_f32 v75, v75, 0x3dd53b94, v90
	v_fmac_f32_e32 v90, 0x3dd53b94, v72
	v_exp_f32_e32 v72, v91
	v_add_f32_e32 v73, v68, v73
	v_exp_f32_e32 v91, v92
	v_add_f32_e32 v73, v69, v73
	v_exp_f32_e32 v92, v93
	v_add_f32_e32 v73, v70, v73
	v_exp_f32_e32 v93, v94
	v_add_f32_e32 v73, v71, v73
	v_exp_f32_e32 v94, v95
	v_add_f32_e32 v73, v72, v73
	v_exp_f32_e32 v95, v180
	v_add_f32_e32 v73, v91, v73
	v_exp_f32_e32 v78, v78
	v_add_f32_e32 v73, v92, v73
	v_exp_f32_e32 v79, v79
	v_add_f32_e32 v73, v93, v73
	v_exp_f32_e32 v80, v80
	v_add_f32_e32 v73, v94, v73
	v_exp_f32_e32 v81, v81
	v_add_f32_e32 v73, v95, v73
	v_exp_f32_e32 v82, v82
	v_add_f32_e32 v73, v78, v73
	v_exp_f32_e32 v83, v83
	v_add_f32_e32 v73, v79, v73
	v_exp_f32_e32 v84, v84
	v_add_f32_e32 v73, v80, v73
	v_exp_f32_e32 v85, v85
	v_add_f32_e32 v73, v81, v73
	v_exp_f32_e32 v86, v86
	v_add_f32_e32 v73, v82, v73
	v_exp_f32_e32 v87, v87
	v_add_f32_e32 v73, v83, v73
	v_exp_f32_e32 v88, v88
	v_add_f32_e32 v73, v84, v73
	v_exp_f32_e32 v89, v89
	v_add_f32_e32 v73, v85, v73
	v_exp_f32_e32 v182, v76
	v_add_f32_e32 v73, v86, v73
	v_exp_f32_e32 v77, v77
	v_add_f32_e32 v73, v87, v73
	v_exp_f32_e32 v183, v74
	v_add_f32_e32 v73, v88, v73
	v_exp_f32_e32 v186, v75
	v_add_f32_e32 v73, v89, v73
	v_add_f32_e32 v73, v182, v73
	v_exp_f32_e32 v90, v90
	v_add_f32_e32 v73, v77, v73
	v_add_f32_e32 v73, v183, v73
	v_add_f32_e32 v73, v186, v73
	v_add_f32_e32 v73, v187, v73
	v_add_f32_e32 v180, v90, v73
	v_mov_b32_e32 v181, v180
	v_cvt_pk_bf16_f32 v64, v64, v65
	v_cvt_pk_bf16_f32 v65, v66, v67
	v_cvt_pk_bf16_f32 v66, v68, v69
	v_cvt_pk_bf16_f32 v67, v70, v71
	v_cvt_pk_bf16_f32 v68, v72, v91
	v_cvt_pk_bf16_f32 v69, v92, v93
	v_cvt_pk_bf16_f32 v70, v94, v95
	v_cvt_pk_bf16_f32 v71, v78, v79
	v_cvt_pk_bf16_f32 v72, v80, v81
	v_cvt_pk_bf16_f32 v73, v82, v83
	v_cvt_pk_bf16_f32 v74, v84, v85
	v_cvt_pk_bf16_f32 v75, v86, v87
	v_cvt_pk_bf16_f32 v76, v88, v89
	v_cvt_pk_bf16_f32 v77, v182, v77
	v_cvt_pk_bf16_f32 v78, v183, v186
	v_cvt_pk_bf16_f32 v79, v187, v90
	s_nop 1
	v_permlane32_swap_b32_e32 v180, v181
	v_permlane32_swap_b32_e32 v64, v66
	v_permlane32_swap_b32_e32 v65, v67
	v_permlane32_swap_b32_e32 v68, v70
	v_permlane32_swap_b32_e32 v69, v71
	v_permlane32_swap_b32_e32 v72, v74
	v_permlane32_swap_b32_e32 v73, v75
	v_permlane32_swap_b32_e32 v76, v78
	v_permlane32_swap_b32_e32 v77, v79
	ds_read_b64_tr_b16 v[80:81], v206 offset:0
	ds_read_b64_tr_b16 v[82:83], v206 offset:0x800
	ds_read_b64_tr_b16 v[84:85], v206 offset:0x1000
	ds_read_b64_tr_b16 v[86:87], v206 offset:0x1800
	ds_read_b64_tr_b16 v[88:89], v206 offset:0x2000
	ds_read_b64_tr_b16 v[90:91], v206 offset:0x2800
	ds_read_b64_tr_b16 v[92:93], v206 offset:0x3000
	ds_read_b64_tr_b16 v[94:95], v206 offset:0x3800
	ds_read_b64_tr_b16 v[186:187], v206 offset:0x200
	ds_read_b64_tr_b16 v[188:189], v206 offset:0xa00
	ds_read_b64_tr_b16 v[190:191], v206 offset:0x1200
	ds_read_b64_tr_b16 v[192:193], v206 offset:0x1a00
	ds_read_b64_tr_b16 v[194:195], v206 offset:0x2200
	ds_read_b64_tr_b16 v[196:197], v206 offset:0x2a00
	ds_read_b64_tr_b16 v[214:215], v206 offset:0x3200
	ds_read_b64_tr_b16 v[216:217], v206 offset:0x3a00
	s_waitcnt lgkmcnt(8)
	s_nop 0
	s_nop 0
	v_mfma_f32_32x32x16_bf16 v[0:15], v[64:67], v[80:83], v[0:15]
	v_mfma_f32_32x32x16_bf16 v[0:15], v[68:71], v[84:87], v[0:15]
	v_mfma_f32_32x32x16_bf16 v[0:15], v[72:75], v[88:91], v[0:15]
	v_mfma_f32_32x32x16_bf16 v[0:15], v[76:79], v[92:95], v[0:15]
	ds_read_b64_tr_b16 v[80:81], v206 offset:0x400
	ds_read_b64_tr_b16 v[82:83], v206 offset:0xc00
	ds_read_b64_tr_b16 v[84:85], v206 offset:0x1400
	ds_read_b64_tr_b16 v[86:87], v206 offset:0x1c00
	ds_read_b64_tr_b16 v[88:89], v206 offset:0x2400
	ds_read_b64_tr_b16 v[90:91], v206 offset:0x2c00
	ds_read_b64_tr_b16 v[92:93], v206 offset:0x3400
	ds_read_b64_tr_b16 v[94:95], v206 offset:0x3c00
	s_waitcnt lgkmcnt(8)
	s_nop 0
	v_mfma_f32_32x32x16_bf16 v[48:63], v[64:67], v[186:189], v[48:63]
	v_mfma_f32_32x32x16_bf16 v[48:63], v[68:71], v[190:193], v[48:63]
	v_mfma_f32_32x32x16_bf16 v[48:63], v[72:75], v[194:197], v[48:63]
	v_mfma_f32_32x32x16_bf16 v[48:63], v[76:79], v[214:217], v[48:63]
	ds_read_b64_tr_b16 v[186:187], v206 offset:0x600
	ds_read_b64_tr_b16 v[188:189], v206 offset:0xe00
	ds_read_b64_tr_b16 v[190:191], v206 offset:0x1600
	ds_read_b64_tr_b16 v[192:193], v206 offset:0x1e00
	ds_read_b64_tr_b16 v[194:195], v206 offset:0x2600
	ds_read_b64_tr_b16 v[196:197], v206 offset:0x2e00
	ds_read_b64_tr_b16 v[214:215], v206 offset:0x3600
	ds_read_b64_tr_b16 v[216:217], v206 offset:0x3e00
	s_waitcnt lgkmcnt(8)
	s_nop 0
	v_mfma_f32_32x32x16_bf16 v[32:47], v[64:67], v[80:83], v[32:47]
	v_mfma_f32_32x32x16_bf16 v[32:47], v[68:71], v[84:87], v[32:47]
	v_mfma_f32_32x32x16_bf16 v[32:47], v[72:75], v[88:91], v[32:47]
	v_mfma_f32_32x32x16_bf16 v[32:47], v[76:79], v[92:95], v[32:47]
	s_waitcnt lgkmcnt(0)
	s_nop 0
	v_mfma_f32_32x32x16_bf16 v[16:31], v[64:67], v[186:189], v[16:31]
	v_mfma_f32_32x32x16_bf16 v[16:31], v[68:71], v[190:193], v[16:31]
	v_mfma_f32_32x32x16_bf16 v[16:31], v[72:75], v[194:197], v[16:31]
	v_mfma_f32_32x32x16_bf16 v[16:31], v[76:79], v[214:217], v[16:31]
	s_waitcnt lgkmcnt(0)
	s_barrier
; __device__ __forceinline__ void partialSM(f32x16& p0, f32x16& p1, float& m_reg, float& mn, float& alpha) {
;   constexpr float C = SCALE * 1.4426950408889634f;
;   float pmax = p0[0];
; #pragma unroll
;   for (int r = 1; r < 16; ++r) pmax = fmaxf(pmax, p0[r]);
; #pragma unroll
;   for (int r = 0; r < 16; ++r) pmax = fmaxf(pmax, p1[r]);
;   { auto rr = __builtin_amdgcn_permlane32_swap(__float_as_uint(pmax), __float_as_uint(pmax), false, false);
;     pmax = fmaxf(__uint_as_float(rr[0]), __uint_as_float(rr[1])); }
;   if (__builtin_expect(__all(pmax - m_reg <= THR / SCALE), 1)) { mn = m_reg; alpha = 1.f; }
;   else { mn = fmaxf(m_reg, pmax); alpha = __builtin_amdgcn_exp2f((m_reg - mn) * C); m_reg = mn; }
	ds_read_b128 v[64:67], v174 offset:12288
	ds_read_b128 v[186:189], v175 offset:12288
	ds_read_b128 v[190:193], v209 offset:57344
	ds_read_b128 v[194:197], v208 offset:57344
	ds_read_b128 v[68:71], v210 offset:57344
	ds_read_b128 v[214:217], v176 offset:12288
	s_waitcnt lgkmcnt(1)
	v_mfma_f32_32x32x16_bf16 v[80:95], v[68:71], v[96:99], 0
	v_mfma_f32_32x32x16_bf16 v[64:79], v[64:67], v[96:99], 0
	ds_read_b128 v[218:221], v207 offset:57344
	ds_read_b128 v[222:225], v177 offset:12288
	v_mfma_f32_32x32x16_bf16 v[80:95], v[190:193], v[100:103], v[80:95]
	v_mfma_f32_32x32x16_bf16 v[64:79], v[186:189], v[100:103], v[64:79]
	ds_read_b128 v[186:189], v210 offset:57472
	ds_read_b128 v[190:193], v174 offset:12416
	v_mfma_f32_32x32x16_bf16 v[80:95], v[194:197], v[104:107], v[80:95]
	s_waitcnt lgkmcnt(4)
	v_mfma_f32_32x32x16_bf16 v[64:79], v[214:217], v[104:107], v[64:79]
	ds_read_b128 v[194:197], v209 offset:57472
	ds_read_b128 v[214:217], v175 offset:12416
	s_waitcnt lgkmcnt(4)
	v_mfma_f32_32x32x16_bf16 v[80:95], v[218:221], v[108:111], v[80:95]
	v_mfma_f32_32x32x16_bf16 v[64:79], v[222:225], v[108:111], v[64:79]
	ds_read_b128 v[218:221], v208 offset:57472
	ds_read_b128 v[222:225], v176 offset:12416
	s_waitcnt lgkmcnt(4)
	v_mfma_f32_32x32x16_bf16 v[80:95], v[186:189], v[112:115], v[80:95]
	v_mfma_f32_32x32x16_bf16 v[64:79], v[190:193], v[112:115], v[64:79]
	ds_read_b128 v[186:189], v207 offset:57472
	ds_read_b128 v[190:193], v177 offset:12416
	s_waitcnt lgkmcnt(4)
	v_mfma_f32_32x32x16_bf16 v[80:95], v[194:197], v[116:119], v[80:95]
	v_mfma_f32_32x32x16_bf16 v[64:79], v[214:217], v[116:119], v[64:79]
	ds_read_b128 v[194:197], v210 offset:57600
	ds_read_b128 v[214:217], v174 offset:12544
	s_waitcnt lgkmcnt(4)
	v_mfma_f32_32x32x16_bf16 v[80:95], v[218:221], v[120:123], v[80:95]
	v_mfma_f32_32x32x16_bf16 v[64:79], v[222:225], v[120:123], v[64:79]
	ds_read_b128 v[218:221], v209 offset:57600
	ds_read_b128 v[222:225], v175 offset:12544
	s_waitcnt lgkmcnt(4)
	v_mfma_f32_32x32x16_bf16 v[80:95], v[186:189], v[124:127], v[80:95]
	v_mfma_f32_32x32x16_bf16 v[64:79], v[190:193], v[124:127], v[64:79]
	ds_read_b128 v[186:189], v208 offset:57600
	ds_read_b128 v[190:193], v176 offset:12544
	s_waitcnt lgkmcnt(4)
	v_mfma_f32_32x32x16_bf16 v[80:95], v[194:197], v[132:135], v[80:95]
	v_mfma_f32_32x32x16_bf16 v[64:79], v[214:217], v[132:135], v[64:79]
	ds_read_b128 v[194:197], v207 offset:57600
	ds_read_b128 v[214:217], v177 offset:12544
	s_waitcnt lgkmcnt(4)
	v_mfma_f32_32x32x16_bf16 v[80:95], v[218:221], v[140:143], v[80:95]
	v_mfma_f32_32x32x16_bf16 v[64:79], v[222:225], v[140:143], v[64:79]
	s_waitcnt lgkmcnt(2)
	v_mfma_f32_32x32x16_bf16 v[80:95], v[186:189], v[128:131], v[80:95]
	v_mfma_f32_32x32x16_bf16 v[64:79], v[190:193], v[128:131], v[64:79]
	s_waitcnt lgkmcnt(0)
	v_mfma_f32_32x32x16_bf16 v[80:95], v[194:197], v[136:139], v[80:95]
	v_mfma_f32_32x32x16_bf16 v[64:79], v[214:217], v[136:139], v[64:79]
	s_nop 9
	v_max3_f32 v182, v80, v81, v82
	v_max3_f32 v182, v182, v83, v84
	v_max3_f32 v183, v64, v65, v66
	v_max3_f32 v182, v182, v85, v86
	v_max3_f32 v183, v183, v67, v68
	v_max3_f32 v182, v182, v87, v88
	v_max3_f32 v183, v183, v69, v70
	v_max3_f32 v182, v182, v89, v90
	v_max3_f32 v183, v183, v71, v72
	v_max3_f32 v182, v182, v91, v92
	v_max3_f32 v183, v183, v73, v74
	v_max3_f32 v182, v182, v93, v94
	v_max3_f32 v183, v183, v75, v76
	v_max3_f32 v183, v183, v77, v78
	v_max3_f32 v182, v182, v95, v79
	v_max_f32_e32 v182, v182, v183
	v_mov_b32_e32 v183, v182
	s_nop 1
	v_permlane32_swap_b32_e32 v182, v183
	s_waitcnt lgkmcnt(0)
	s_barrier
	v_max_f32_e32 v182, v182, v183
	s_waitcnt vmcnt(0)
	v_sub_f32_e32 v183, v182, v178
	v_cmp_ge_f32_e64 s[8:9], s30, v183
	s_cmpk_gt_u32 s19, 0xfd
	ds_write_b128 v212, v[144:147]
	ds_write_b128 v212, v[148:151] offset:1024
	ds_write_b128 v211, v[152:155] offset:32768
	ds_write_b128 v211, v[156:159] offset:32896
	ds_write_b128 v211, v[160:163] offset:33024
	s_cbranch_scc1 .LBB0_465
	v_add_co_u32_e32 v148, vcc, 0x28780000, v170
	s_nop 1
	v_addc_co_u32_e32 v149, vcc, 0, v171, vcc
	v_add_co_u32_e32 v160, vcc, 0x1b360000, v168
	global_load_dwordx4 v[144:147], v[148:149], off offset:256
	s_nop 0
	global_load_dwordx4 v[148:151], v[148:149], off offset:384
	v_addc_co_u32_e32 v161, vcc, 0, v169, vcc
	global_load_dwordx4 v[152:155], v[160:161], off
	global_load_dwordx4 v[156:159], v[160:161], off offset:128
	s_nop 0
	global_load_dwordx4 v[160:163], v[160:161], off offset:256

; #define QSTEP(d, A, B, NA, NB) do { if ((d) + 2 < 12) { NA = KLD((d) + 2, 0); NB = KLD((d) + 2, 1); } SBAR(); \
;     p0 = __builtin_amdgcn_mfma_f32_32x32x16_bf16(A, qr[d], p0, 0, 0, 0); p1 = __builtin_amdgcn_mfma_f32_32x32x16_bf16(B, qr[d], p1, 0, 0, 0); SBAR(); } while (0)
; __device__ __forceinline__ void partialSM(f32x16& p0, f32x16& p1, float& m_reg, float& mn, float& alpha) {
;   constexpr float C = SCALE * 1.4426950408889634f;
;   float pmax = p0[0];
; #pragma unroll
;   for (int r = 1; r < 16; ++r) pmax = fmaxf(pmax, p0[r]);
; #pragma unroll
;   for (int r = 0; r < 16; ++r) pmax = fmaxf(pmax, p1[r]);
;   { auto rr = __builtin_amdgcn_permlane32_swap(__float_as_uint(pmax), __float_as_uint(pmax), false, false);
;     pmax = fmaxf(__uint_as_float(rr[0]), __uint_as_float(rr[1])); }
;   if (__builtin_expect(__all(pmax - m_reg <= THR / SCALE), 1)) { mn = m_reg; alpha = 1.f; }
;   else { mn = fmaxf(m_reg, pmax); alpha = __builtin_amdgcn_exp2f((m_reg - mn) * C); m_reg = mn; }
; __device__ __forceinline__ void qkt2(f32x16& p0, f32x16& p1, const char* Ks, const bf16x8* qr, const int* kb4) {
;     ...
;   p0 = f32x16{}; p1 = f32x16{};
;   bf16x8 a0 = KLD(0, 0), b0 = KLD(0, 1), a1 = KLD(1, 0), b1 = KLD(1, 1), a2, b2;
;     ...
;   QSTEP(0, a0, b0, a2, b2); QSTEP(1, a1, b1, a0, b0); QSTEP(2, a2, b2, a1, b1);
;   QSTEP(3, a0, b0, a2, b2); QSTEP(4, a1, b1, a0, b0); QSTEP(5, a2, b2, a1, b1);
;   QSTEP(6, a0, b0, a2, b2); QSTEP(7, a1, b1, a0, b0); QSTEP(8, a2, b2, a1, b1);
;   QSTEP(9, a0, b0, a2, b2); QSTEP(10, a1, b1, a0, b0); QSTEP(11, a2, b2, a1, b1);
;     ...
; }
.LBB0_471:
	ds_read_b128 v[64:67], v210 offset:32768
	ds_read_b128 v[68:71], v210 offset:45056
	s_waitcnt vmcnt(4)
	ds_read_b128 v[144:147], v209 offset:32768
	s_waitcnt vmcnt(3)
	ds_read_b128 v[148:151], v209 offset:45056
	s_waitcnt vmcnt(2)
	ds_read_b128 v[152:155], v208 offset:32768
	s_waitcnt vmcnt(1)
	ds_read_b128 v[156:159], v208 offset:45056
	s_waitcnt lgkmcnt(5)
	v_mfma_f32_32x32x16_bf16 v[80:95], v[64:67], v[96:99], 0
	s_waitcnt lgkmcnt(4)
	v_mfma_f32_32x32x16_bf16 v[64:79], v[68:71], v[96:99], 0
	ds_read_b128 v[96:99], v207 offset:32768
	s_waitcnt vmcnt(0)
	ds_read_b128 v[160:163], v207 offset:45056
	s_waitcnt lgkmcnt(5)
	v_mfma_f32_32x32x16_bf16 v[80:95], v[144:147], v[100:103], v[80:95]
	s_waitcnt lgkmcnt(4)
	v_mfma_f32_32x32x16_bf16 v[64:79], v[148:151], v[100:103], v[64:79]
	ds_read_b128 v[100:103], v210 offset:32896
	ds_read_b128 v[144:147], v210 offset:45184
	s_waitcnt lgkmcnt(5)
	v_mfma_f32_32x32x16_bf16 v[80:95], v[152:155], v[104:107], v[80:95]
	s_waitcnt lgkmcnt(4)
	v_mfma_f32_32x32x16_bf16 v[64:79], v[156:159], v[104:107], v[64:79]
	ds_read_b128 v[104:107], v209 offset:32896
	ds_read_b128 v[148:151], v209 offset:45184
	s_waitcnt lgkmcnt(5)
	v_mfma_f32_32x32x16_bf16 v[80:95], v[96:99], v[108:111], v[80:95]
	s_waitcnt lgkmcnt(4)
	v_mfma_f32_32x32x16_bf16 v[64:79], v[160:163], v[108:111], v[64:79]
	ds_read_b128 v[96:99], v208 offset:32896
	ds_read_b128 v[108:111], v208 offset:45184
	s_waitcnt lgkmcnt(5)
	v_mfma_f32_32x32x16_bf16 v[80:95], v[100:103], v[112:115], v[80:95]
	s_waitcnt lgkmcnt(4)
	v_mfma_f32_32x32x16_bf16 v[64:79], v[144:147], v[112:115], v[64:79]
	ds_read_b128 v[100:103], v207 offset:32896
	ds_read_b128 v[112:115], v207 offset:45184
	s_waitcnt lgkmcnt(5)
	v_mfma_f32_32x32x16_bf16 v[80:95], v[104:107], v[116:119], v[80:95]
	s_waitcnt lgkmcnt(4)
	v_mfma_f32_32x32x16_bf16 v[64:79], v[148:151], v[116:119], v[64:79]
	ds_read_b128 v[104:107], v210 offset:33024
	ds_read_b128 v[116:119], v210 offset:45312
	s_waitcnt lgkmcnt(5)
	v_mfma_f32_32x32x16_bf16 v[80:95], v[96:99], v[120:123], v[80:95]
	s_waitcnt lgkmcnt(4)
	v_mfma_f32_32x32x16_bf16 v[64:79], v[108:111], v[120:123], v[64:79]
	ds_read_b128 v[96:99], v209 offset:33024
	ds_read_b128 v[108:111], v209 offset:45312
	s_waitcnt lgkmcnt(5)
	v_mfma_f32_32x32x16_bf16 v[80:95], v[100:103], v[124:127], v[80:95]
	s_waitcnt lgkmcnt(4)
	v_mfma_f32_32x32x16_bf16 v[64:79], v[112:115], v[124:127], v[64:79]
	ds_read_b128 v[100:103], v208 offset:33024
	ds_read_b128 v[112:115], v208 offset:45312
	s_waitcnt lgkmcnt(5)
	v_mfma_f32_32x32x16_bf16 v[80:95], v[104:107], v[132:135], v[80:95]
	s_waitcnt lgkmcnt(4)
	v_mfma_f32_32x32x16_bf16 v[64:79], v[116:119], v[132:135], v[64:79]
	ds_read_b128 v[104:107], v207 offset:33024
	ds_read_b128 v[116:119], v207 offset:45312
	s_waitcnt lgkmcnt(5)
	v_mfma_f32_32x32x16_bf16 v[80:95], v[96:99], v[140:143], v[80:95]
	s_waitcnt lgkmcnt(4)
	v_mfma_f32_32x32x16_bf16 v[64:79], v[108:111], v[140:143], v[64:79]
	s_waitcnt lgkmcnt(3)
	v_mfma_f32_32x32x16_bf16 v[80:95], v[100:103], v[128:131], v[80:95]
	s_waitcnt lgkmcnt(2)
	v_mfma_f32_32x32x16_bf16 v[64:79], v[112:115], v[128:131], v[64:79]
	s_waitcnt lgkmcnt(1)
	v_mfma_f32_32x32x16_bf16 v[80:95], v[104:107], v[136:139], v[80:95]
	s_waitcnt lgkmcnt(0)
	v_mfma_f32_32x32x16_bf16 v[64:79], v[116:119], v[136:139], v[64:79]
	s_nop 9
	v_max3_f32 v96, v80, v81, v82
	v_max3_f32 v96, v96, v83, v84
	v_max3_f32 v97, v64, v65, v66
	v_max3_f32 v96, v96, v85, v86
	v_max3_f32 v97, v97, v67, v68
	v_max3_f32 v96, v96, v87, v88
	v_max3_f32 v97, v97, v69, v70
	v_max3_f32 v96, v96, v89, v90
	v_max3_f32 v97, v97, v71, v72
	v_max3_f32 v96, v96, v91, v92
	v_max3_f32 v97, v97, v73, v74
	v_max3_f32 v96, v96, v93, v94
	v_max3_f32 v97, v97, v75, v76
	v_max3_f32 v97, v97, v77, v78
	v_max3_f32 v96, v96, v95, v79
	v_max_f32_e32 v96, v96, v97
	v_mov_b32_e32 v97, v96
	s_nop 1
	v_permlane32_swap_b32_e32 v96, v97
	v_max_f32_e32 v96, v96, v97
	v_max_f32_e32 v97, v178, v178
	v_max_f32_e32 v97, v97, v96
	v_sub_f32_e32 v98, v96, v178
	v_sub_f32_e32 v96, v178, v97
	v_mul_f32_e32 v96, 0x3dd53b94, v96
	v_exp_f32_e32 v96, v96
	v_cmp_ge_f32_e32 vcc, s30, v98
	s_cmp_eq_u64 vcc, exec
	s_cselect_b64 s[8:9], -1, 0
	s_waitcnt lgkmcnt(0)
	s_barrier
	v_cndmask_b32_e64 v96, v96, 1.0, s[8:9]
	v_cmp_gt_f32_e32 vcc, 1.0, v96
	s_cbranch_vccz .LBB0_475
	s_and_saveexec_b64 s[0:1], s[6:7]
	ds_write_b32 v205, v96 offset:128
	s_or_b64 exec, exec, s[0:1]
	s_waitcnt lgkmcnt(0)
	v_add_u32_e32 v110, s3, v184
	ds_read_b128 v[98:101], v110 offset:224
	ds_read_b128 v[102:105], v110 offset:192
	ds_read_b128 v[106:109], v110 offset:160
	ds_read_b128 v[110:113], v110 offset:128
	s_waitcnt lgkmcnt(3)
	v_pk_mul_f32 v[12:13], v[12:13], v[98:99]
	s_waitcnt lgkmcnt(2)
	v_pk_mul_f32 v[8:9], v[8:9], v[102:103]
	s_waitcnt lgkmcnt(1)
	v_pk_mul_f32 v[4:5], v[4:5], v[106:107]
	v_pk_mul_f32 v[14:15], v[14:15], v[100:101]
	v_pk_mul_f32 v[10:11], v[10:11], v[104:105]
	v_pk_mul_f32 v[6:7], v[6:7], v[108:109]
	s_waitcnt lgkmcnt(0)
	v_pk_mul_f32 v[2:3], v[2:3], v[112:113]
	v_pk_mul_f32 v[0:1], v[0:1], v[110:111]
	v_pk_mul_f32 v[60:61], v[60:61], v[98:99]
	v_pk_mul_f32 v[56:57], v[56:57], v[102:103]
	v_pk_mul_f32 v[52:53], v[52:53], v[106:107]
	v_pk_mul_f32 v[62:63], v[62:63], v[100:101]
	v_pk_mul_f32 v[58:59], v[58:59], v[104:105]
	v_pk_mul_f32 v[54:55], v[54:55], v[108:109]
	v_pk_mul_f32 v[50:51], v[50:51], v[112:113]
	v_pk_mul_f32 v[48:49], v[48:49], v[110:111]
	v_pk_mul_f32 v[44:45], v[44:45], v[98:99]
	v_pk_mul_f32 v[40:41], v[40:41], v[102:103]
	v_pk_mul_f32 v[36:37], v[36:37], v[106:107]
	v_pk_mul_f32 v[46:47], v[46:47], v[100:101]
	v_pk_mul_f32 v[42:43], v[42:43], v[104:105]
	v_pk_mul_f32 v[38:39], v[38:39], v[108:109]
	v_pk_mul_f32 v[34:35], v[34:35], v[112:113]
	v_pk_mul_f32 v[32:33], v[32:33], v[110:111]
	v_pk_mul_f32 v[28:29], v[28:29], v[98:99]
	v_pk_mul_f32 v[24:25], v[24:25], v[102:103]
	v_pk_mul_f32 v[20:21], v[20:21], v[106:107]
	v_pk_mul_f32 v[30:31], v[30:31], v[100:101]
	v_pk_mul_f32 v[26:27], v[26:27], v[104:105]
	v_pk_mul_f32 v[22:23], v[22:23], v[108:109]
	v_pk_mul_f32 v[18:19], v[18:19], v[112:113]
	v_pk_mul_f32 v[16:17], v[16:17], v[110:111]
